# P1 column tiles taken in reverse order so q/k/v are the most recently written data when attention starts
# speedup vs baseline: 1.0086x; 1.0086x over previous
.LBB0_195:
	s_or_b64 exec, exec, s[4:5]
	v_mov_b32_e32 v8, v254
	s_cmpk_lt_i32 s2, 0xa00
	s_waitcnt lgkmcnt(0)
	s_barrier
	s_cselect_b64 s[4:5], -1, 0
	s_cmpk_gt_i32 s2, 0x9ff
	v_readfirstlane_b32 s14, v8
	s_cbranch_scc1 .LBB0_197
	s_ashr_i32 s3, s2, 31
	s_lshr_b32 s3, s3, 29
	s_add_i32 s3, s2, s3
	s_ashr_i32 s6, s3, 3
	s_and_b32 s3, s3, -8
	s_sub_i32 s3, s2, s3
	s_cmp_lt_i32 s3, 0
	s_movk_i32 s7, 0x141
	s_cselect_b32 s7, s7, 0x140
	s_mul_i32 s3, s7, s3
	s_add_i32 s3, s3, s6
	s_mul_hi_i32 s6, s3, 0x66666667
	s_lshr_b32 s7, s6, 31
	s_ashr_i32 s6, s6, 6
	s_add_i32 s6, s6, s7
	s_lshl_b32 s7, s6, 3
	s_mulk_i32 s6, 0xa0
	s_sub_i32 s3, s3, s6
	s_sext_i32_i16 s6, s3
	s_bfe_u32 s6, s6, 0x3001c
	s_add_i32 s6, s3, s6
	s_sext_i32_i16 s8, s6
	s_and_b32 s6, s6, 0xfff8
	s_sub_i32 s3, s3, s6
	s_sext_i32_i16 s3, s3
	s_add_i32 s6, s7, s3
	s_ashr_i32 s36, s8, 3
	s_sub_i32 s36, 19, s36

.LBB0_203:
	s_add_i32 s87, s87, 1
	s_mul_i32 s4, s87, s33
	s_mul_hi_u32 s5, s87, s38
	s_add_i32 s5, s5, s4
	s_mul_i32 s4, s87, s38
	s_add_u32 s64, s4, s2
	s_addc_u32 s65, s5, s3
	v_cmp_gt_i64_e32 vcc, s[64:65], v[158:159]
	v_cmp_lt_i64_e64 s[4:5], s[64:65], v[156:157]
	s_cbranch_vccnz .LBB0_205
	s_ashr_i32 s37, s64, 31
	s_lshr_b32 s37, s37, 29
	s_add_i32 s37, s64, s37
	s_ashr_i32 s60, s37, 3
	s_and_b32 s37, s37, -8
	s_sub_i32 s37, s64, s37
	s_cmp_lt_i32 s37, 0
	s_movk_i32 s61, 0x141
	s_cselect_b32 s61, s61, 0x140
	s_mul_i32 s37, s61, s37
	s_add_i32 s37, s37, s60
	s_mul_hi_i32 s60, s37, 0x66666667
	s_lshr_b32 s61, s60, 31
	s_ashr_i32 s60, s60, 6
	s_add_i32 s60, s60, s61
	s_lshl_b32 s61, s60, 3
	s_sub_i32 s62, 0x80, s61
	s_min_i32 s62, s62, 8
	s_abs_i32 s63, s62
	s_sub_i32 s65, 0, s63
	s_mulk_i32 s60, 0xa0
	s_sub_i32 s37, s37, s60
	s_abs_i32 s60, s37
	s_xor_b32 s64, s37, s62
	s_ashr_i32 s64, s64, 31
	s_mov_b32 s70, 0x1fffffc0
	s_mul_i32 s65, s65, s70
	s_mul_hi_u32 s65, s70, s65
	s_add_i32 s70, s70, s65
	s_mul_hi_u32 s65, s60, s70
	s_mul_i32 s70, s65, s63
	s_sub_i32 s60, s60, s70
	s_add_i32 s71, s65, 1
	s_sub_i32 s70, s60, s63
	s_cmp_ge_u32 s60, s63
	s_cselect_b32 s65, s71, s65
	s_cselect_b32 s60, s70, s60
	s_add_i32 s70, s65, 1
	s_cmp_ge_u32 s60, s63
	s_cselect_b32 s60, s70, s65
	s_xor_b32 s60, s60, s64
	s_sub_i32 s60, s60, s64
	s_mul_i32 s62, s60, s62
	s_sub_i32 s37, s37, s62
	s_add_i32 s62, s37, s61
	s_sub_i32 s60, 19, s60

.LBB0_1055:
	s_or_b64 exec, exec, s[0:1]
	v_readlane_b32 s0, v255, 16
	v_mov_b32_e32 v8, v254
	v_readlane_b32 s1, v255, 17
	s_waitcnt lgkmcnt(0)
	s_barrier
	s_and_b64 vcc, exec, s[0:1]
	v_readfirstlane_b32 s0, v8
	s_cbranch_vccnz .LBB0_1057
	s_lshr_b32 s1, s3, 29
	s_add_i32 s1, s2, s1
	s_ashr_i32 s4, s1, 3
	s_and_b32 s1, s1, -8
	s_sub_i32 s1, s2, s1
	s_cmp_lt_i32 s1, 0
	s_movk_i32 s5, 0x141
	s_cselect_b32 s5, s5, 0x140
	s_mul_i32 s1, s5, s1
	s_add_i32 s1, s1, s4
	s_mul_hi_i32 s4, s1, 0x66666667
	s_lshr_b32 s5, s4, 31
	s_ashr_i32 s4, s4, 6
	s_add_i32 s4, s4, s5
	s_lshl_b32 s5, s4, 3
	s_mulk_i32 s4, 0xa0
	s_sub_i32 s1, s1, s4
	s_sext_i32_i16 s4, s1
	s_bfe_u32 s4, s4, 0x3001c
	s_add_i32 s4, s1, s4
	s_sext_i32_i16 s6, s4
	s_and_b32 s4, s4, 0xfff8
	s_sub_i32 s1, s1, s4
	s_sext_i32_i16 s1, s1
	s_add_i32 s36, s5, s1
	s_ashr_i32 s40, s6, 3
	s_sub_i32 s40, 19, s40

.LBB0_1063:
	s_add_i32 s85, s85, 1
	s_mul_i32 s0, s85, s33
	s_mul_hi_u32 s8, s85, s38
	s_add_i32 s8, s8, s0
	s_mul_i32 s0, s85, s38
	s_add_u32 s66, s0, s2
	s_addc_u32 s67, s8, s3
	v_cmp_gt_i64_e32 vcc, s[66:67], v[190:191]
	v_cmp_lt_i64_e64 s[8:9], s[66:67], v[188:189]
	s_cbranch_vccnz .LBB0_1065
	s_ashr_i32 s0, s66, 31
	s_lshr_b32 s0, s0, 29
	s_add_i32 s0, s66, s0
	s_ashr_i32 s37, s0, 3
	s_and_b32 s0, s0, -8
	s_sub_i32 s0, s66, s0
	s_cmp_lt_i32 s0, 0
	s_movk_i32 s60, 0x141
	s_cselect_b32 s60, s60, 0x140
	s_mul_i32 s0, s60, s0
	s_add_i32 s0, s0, s37
	s_mul_hi_i32 s37, s0, 0x66666667
	s_lshr_b32 s60, s37, 31
	s_ashr_i32 s37, s37, 6
	s_add_i32 s37, s37, s60
	s_lshl_b32 s61, s37, 3
	s_sub_i32 s60, 0x80, s61
	s_min_i32 s66, s60, 8
	s_abs_i32 s60, s66
	v_cvt_f32_u32_e32 v0, s60
	s_sub_i32 s74, 0, s60
	s_mulk_i32 s37, 0xa0
	s_sub_i32 s0, s0, s37
	v_rcp_iflag_f32_e32 v0, v0
	s_abs_i32 s37, s0
	s_xor_b32 s67, s0, s66
	s_ashr_i32 s67, s67, 31
	v_mul_f32_e32 v0, 0x4f7ffffe, v0
	v_cvt_u32_f32_e32 v0, v0
	s_nop 0
	v_readfirstlane_b32 s75, v0
	s_mul_i32 s74, s74, s75
	s_mul_hi_u32 s74, s75, s74
	s_add_i32 s75, s75, s74
	s_mul_hi_u32 s74, s37, s75
	s_mul_i32 s75, s74, s60
	s_sub_i32 s37, s37, s75
	s_add_i32 s82, s74, 1
	s_sub_i32 s75, s37, s60
	s_cmp_ge_u32 s37, s60
	s_cselect_b32 s74, s82, s74
	s_cselect_b32 s37, s75, s37
	s_add_i32 s75, s74, 1
	s_cmp_ge_u32 s37, s60
	s_cselect_b32 s37, s75, s74
	s_xor_b32 s37, s37, s67
	s_sub_i32 s60, s37, s67
	s_mul_i32 s37, s60, s66
	s_sub_i32 s0, s0, s37
	s_add_i32 s82, s0, s61
	s_sub_i32 s60, 19, s60

.LBB0_1923:
	s_add_i32 s85, s85, 1
	s_mul_i32 s0, s85, s33
	s_mul_hi_u32 s10, s85, s38
	s_add_i32 s10, s10, s0
	s_mul_i32 s0, s85, s38
	s_add_u32 s66, s0, s2
	s_addc_u32 s67, s10, s3
	v_cmp_gt_i64_e32 vcc, s[66:67], v[190:191]
	v_cmp_lt_i64_e64 s[10:11], s[66:67], v[188:189]
	s_cbranch_vccnz .LBB0_1925
	s_ashr_i32 s0, s66, 31
	s_lshr_b32 s0, s0, 29
	s_add_i32 s0, s66, s0
	s_ashr_i32 s37, s0, 3
	s_and_b32 s0, s0, -8
	s_sub_i32 s0, s66, s0
	s_cmp_lt_i32 s0, 0
	s_movk_i32 s60, 0x141
	s_cselect_b32 s60, s60, 0x140
	s_mul_i32 s0, s60, s0
	s_add_i32 s0, s0, s37
	s_mul_hi_i32 s37, s0, 0x66666667
	s_lshr_b32 s60, s37, 31
	s_ashr_i32 s37, s37, 6
	s_add_i32 s37, s37, s60
	s_lshl_b32 s61, s37, 3
	s_sub_i32 s60, 0x80, s61
	s_min_i32 s66, s60, 8
	s_abs_i32 s60, s66
	v_cvt_f32_u32_e32 v0, s60
	s_sub_i32 s74, 0, s60
	s_mulk_i32 s37, 0xa0
	s_sub_i32 s0, s0, s37
	v_rcp_iflag_f32_e32 v0, v0
	s_abs_i32 s37, s0
	s_xor_b32 s67, s0, s66
	s_ashr_i32 s67, s67, 31
	v_mul_f32_e32 v0, 0x4f7ffffe, v0
	v_cvt_u32_f32_e32 v0, v0
	s_nop 0
	v_readfirstlane_b32 s75, v0
	s_mul_i32 s74, s74, s75
	s_mul_hi_u32 s74, s75, s74
	s_add_i32 s75, s75, s74
	s_mul_hi_u32 s74, s37, s75
	s_mul_i32 s75, s74, s60
	s_sub_i32 s37, s37, s75
	s_add_i32 s82, s74, 1
	s_sub_i32 s75, s37, s60
	s_cmp_ge_u32 s37, s60
	s_cselect_b32 s74, s82, s74
	s_cselect_b32 s37, s75, s37
	s_add_i32 s75, s74, 1
	s_cmp_ge_u32 s37, s60
	s_cselect_b32 s37, s75, s74
	s_xor_b32 s37, s37, s67
	s_sub_i32 s60, s37, s67
	s_mul_i32 s37, s60, s66
	s_sub_i32 s0, s0, s37
	s_add_i32 s82, s0, s61
	s_sub_i32 s60, 19, s60

.LBB0_2787:
	s_add_i32 s79, s79, 1
	s_mul_i32 s0, s79, s33
	s_mul_hi_u32 s10, s79, s38
	s_add_i32 s10, s10, s0
	s_mul_i32 s0, s79, s38
	s_add_u32 s26, s0, s2
	s_addc_u32 s27, s10, s3
	v_cmp_gt_i64_e32 vcc, s[26:27], v[190:191]
	v_cmp_lt_i64_e64 s[10:11], s[26:27], v[188:189]
	s_cbranch_vccnz .LBB0_2789
	s_ashr_i32 s0, s26, 31
	s_lshr_b32 s0, s0, 29
	s_add_i32 s0, s26, s0
	s_ashr_i32 s22, s0, 3
	s_and_b32 s0, s0, -8
	s_sub_i32 s0, s26, s0
	s_cmp_lt_i32 s0, 0
	s_movk_i32 s23, 0x141
	s_cselect_b32 s23, s23, 0x140
	s_mul_i32 s0, s23, s0
	s_add_i32 s0, s0, s22
	s_mul_hi_i32 s22, s0, 0x66666667
	s_lshr_b32 s23, s22, 31
	s_ashr_i32 s22, s22, 6
	s_add_i32 s22, s22, s23
	s_lshl_b32 s23, s22, 3
	s_sub_i32 s24, 0x80, s23
	s_min_i32 s24, s24, 8
	s_abs_i32 s25, s24
	s_sub_i32 s27, 0, s25
	s_mulk_i32 s22, 0xa0
	s_sub_i32 s0, s0, s22
	s_abs_i32 s22, s0
	s_xor_b32 s26, s0, s24
	s_ashr_i32 s26, s26, 31
	s_mov_b32 s34, 0x1fffffc0
	s_mul_i32 s27, s27, s34
	s_mul_hi_u32 s27, s34, s27
	s_add_i32 s34, s34, s27
	s_mul_hi_u32 s27, s22, s34
	s_mul_i32 s34, s27, s25
	s_sub_i32 s22, s22, s34
	s_add_i32 s35, s27, 1
	s_sub_i32 s34, s22, s25
	s_cmp_ge_u32 s22, s25
	s_cselect_b32 s27, s35, s27
	s_cselect_b32 s22, s34, s22
	s_add_i32 s34, s27, 1
	s_cmp_ge_u32 s22, s25
	s_cselect_b32 s22, s34, s27
	s_xor_b32 s22, s22, s26
	s_sub_i32 s22, s22, s26
	s_mul_i32 s24, s22, s24
	s_sub_i32 s0, s0, s24
	s_add_i32 s24, s0, s23
	s_sub_i32 s22, 19, s22
